# prologue de-serialisation in the attention Q-tile load: the three later q_g vector loads issued with the Q row loads (scratch regs), 4th rope-table load before the first wait
# baseline (speedup 1.0000x reference)
; #define LAS __attribute__((address_space(3)))
; DI float red4(float x) { x += dppmov<0xB1>(x); x += dppmov<0x4E>(x); return x; }
; DI int tid_opaque() { int t = threadIdx.x; asm volatile("" : "+v"(t)); return t; }
; DI void attn_load_head(const bf16_t* Pb, int coloff, int b, int t0, const float* g, bool rope, float scale, const float* tab, LAS bf16_t* dst) {
;     const int tid = tid_opaque(), row = tid >> 2, q4 = tid & 3; const int t = t0 + row; const size_t mrow = (size_t)b * T + t;
;     const bf16_t* src = Pb + mrow * PW + coloff;
;     float y[4][4]; float ss = 0.f;
; #pragma unroll
;     for (int c = 0; c < 4; ++c) { const u32x2 u = *(const u32x2*)(src + c * 16 + q4 * 4); y[c][0] = bflo(u.x); y[c][1] = bfhi(u.x); y[c][2] = bflo(u.y); y[c][3] = bfhi(u.y);
; #pragma unroll
;         for (int e = 0; e < 4; ++e) ss += y[c][e] * y[c][e]; }
;     ss = red4(ss); const float rstd = rsqrtf(ss * (1.f / 64.f) + 1e-6f);
; #pragma unroll
;     for (int c = 0; c < 4; ++c)
; #pragma unroll
;         for (int e = 0; e < 4; ++e) y[c][e] = y[c][e] * rstd * g[c * 16 + q4 * 4 + e];
;     if (rope) { const int pos = t - LC, rp = pos >> 6, cp = pos & 63;
; #pragma unroll
;         for (int e = 0; e < 4; ++e) { const int i = q4 * 4 + e;
;             { const float co = tab[rp * 16 + i], si = tab[1024 + rp * 16 + i]; const float x1 = y[0][e], x2 = y[1][e]; y[0][e] = x1 * co - x2 * si; y[1][e] = x1 * si + x2 * co; }
;             { const float co = tab[cp * 16 + i], si = tab[1024 + cp * 16 + i]; const float x1 = y[2][e], x2 = y[3][e]; y[2][e] = x1 * co - x2 * si; y[3][e] = x1 * si + x2 * co; } } }
.LBB0_606:
	v_mov_b32_e32 v0, v182
	s_mov_b32 s26, 0x800000
	v_ashrrev_i32_e32 v25, 2, v0
	v_mad_i64_i32 v[2:3], s[36:37], v25, s78, 0
	v_and_b32_e32 v26, 3, v0
	s_add_u32 s36, s22, s18
	v_lshl_or_b32 v2, v26, 3, v2
	s_addc_u32 s37, s23, s19
	v_lshl_add_u64 v[2:3], s[36:37], 0, v[2:3]
	global_load_dwordx2 v[16:17], v[2:3], off offset:-64
	global_load_dwordx2 v[18:19], v[2:3], off offset:-32
	global_load_dwordx2 v[6:7], v[2:3], off
	global_load_dwordx2 v[8:9], v[2:3], off offset:32
	v_lshlrev_b32_e32 v0, 4, v26
	global_load_dwordx4 v[2:5], v0, s[16:17] offset:128
	global_load_dwordx4 v[54:57], v0, s[16:17] offset:192
	global_load_dwordx4 v[58:61], v0, s[16:17]
	global_load_dwordx4 v[62:65], v0, s[16:17] offset:64
	s_waitcnt vmcnt(7)
	v_and_b32_e32 v43, 0xffff0000, v17
	v_lshlrev_b32_e32 v42, 16, v17
	s_waitcnt vmcnt(5)
	v_and_b32_e32 v11, 0xffff0000, v7
	v_lshlrev_b32_e32 v10, 16, v7
	s_waitcnt vmcnt(4)
	v_and_b32_e32 v23, 0xffff0000, v9
	v_lshlrev_b32_e32 v22, 16, v9
	v_and_b32_e32 v35, 0xffff0000, v6
	v_lshlrev_b32_e32 v34, 16, v6
	v_and_b32_e32 v39, 0xffff0000, v8
	v_lshlrev_b32_e32 v38, 16, v8
	s_waitcnt vmcnt(0)
	v_mov_b64_e32 v[6:7], v[54:55]
	v_mov_b64_e32 v[8:9], v[56:57]
	v_mov_b64_e32 v[12:13], v[58:59]
	v_mov_b64_e32 v[14:15], v[60:61]
	v_mov_b64_e32 v[28:29], v[62:63]
	v_mov_b64_e32 v[30:31], v[64:65]
	v_and_b32_e32 v17, 0xffff0000, v16
	v_lshlrev_b32_e32 v16, 16, v16
	v_pk_mul_f32 v[50:51], v[16:17], v[16:17]
	v_pk_mul_f32 v[44:45], v[42:43], v[42:43]
	v_add_f32_e32 v0, v50, v51
	v_and_b32_e32 v53, 0xffff0000, v18
	v_lshlrev_b32_e32 v52, 16, v18
	v_add_f32_e32 v0, v44, v0
	v_and_b32_e32 v47, 0xffff0000, v19
	v_lshlrev_b32_e32 v46, 16, v19
	v_pk_mul_f32 v[18:19], v[52:53], v[52:53]
	v_add_f32_e32 v0, v45, v0
	v_add_f32_e32 v0, v18, v0
	v_pk_mul_f32 v[48:49], v[46:47], v[46:47]
	v_add_f32_e32 v0, v19, v0
	v_add_f32_e32 v0, v48, v0
	v_pk_mul_f32 v[36:37], v[34:35], v[34:35]
	v_add_f32_e32 v0, v49, v0
	v_add_f32_e32 v0, v36, v0
	v_pk_mul_f32 v[20:21], v[10:11], v[10:11]
	v_add_f32_e32 v0, v37, v0
	v_add_f32_e32 v0, v20, v0
	v_pk_mul_f32 v[40:41], v[38:39], v[38:39]
	v_add_f32_e32 v0, v21, v0
	v_add_f32_e32 v0, v40, v0
	v_pk_mul_f32 v[32:33], v[22:23], v[22:23]
	v_add_f32_e32 v0, v41, v0
	v_add_f32_e32 v0, v32, v0
	v_add_f32_e32 v0, v33, v0
	s_nop 1
	v_add_f32_dpp v0, v0, v0 quad_perm:[1,0,3,2] row_mask:0xf bank_mask:0xf bound_ctrl:1
	s_nop 1
	v_add_f32_dpp v0, v0, v0 quad_perm:[2,3,0,1] row_mask:0xf bank_mask:0xf bound_ctrl:1
	v_fmamk_f32 v0, v0, 0x3c800000, v183
	v_cmp_gt_f32_e32 vcc, s26, v0
	v_mul_f32_e32 v18, 0x4b800000, v0
	s_nop 0
	v_cndmask_b32_e32 v0, v0, v18, vcc
	v_rsq_f32_e32 v0, v0
	s_nop 0
	v_mul_f32_e32 v18, 0x45800000, v0
	v_cndmask_b32_e32 v0, v0, v18, vcc
	v_pk_mul_f32 v[16:17], v[0:1], v[16:17] op_sel_hi:[0,1]
	s_andn2_b64 vcc, exec, s[4:5]
	s_waitcnt vmcnt(1)
	v_pk_mul_f32 v[20:21], v[12:13], v[16:17]
	v_pk_mul_f32 v[12:13], v[0:1], v[42:43] op_sel_hi:[0,1]
	v_pk_mul_f32 v[18:19], v[14:15], v[12:13]
	v_pk_mul_f32 v[12:13], v[0:1], v[52:53] op_sel_hi:[0,1]
	s_waitcnt vmcnt(0)
	v_pk_mul_f32 v[16:17], v[28:29], v[12:13]
	v_pk_mul_f32 v[12:13], v[0:1], v[46:47] op_sel_hi:[0,1]
	v_pk_mul_f32 v[14:15], v[30:31], v[12:13]
	v_pk_mul_f32 v[12:13], v[0:1], v[34:35] op_sel_hi:[0,1]
	v_pk_mul_f32 v[12:13], v[2:3], v[12:13]
	v_pk_mul_f32 v[2:3], v[0:1], v[10:11] op_sel_hi:[0,1]
	v_pk_mul_f32 v[10:11], v[4:5], v[2:3]
	v_pk_mul_f32 v[2:3], v[0:1], v[38:39] op_sel_hi:[0,1]
	v_pk_mul_f32 v[4:5], v[6:7], v[2:3]
	v_pk_mul_f32 v[2:3], v[0:1], v[22:23] op_sel_hi:[0,1]
	v_pk_mul_f32 v[2:3], v[8:9], v[2:3]
	s_cbranch_vccnz .LBB0_605
	v_add_u32_e32 v6, s7, v25
	v_add_u32_e32 v6, 0xffffff00, v6
	v_lshlrev_b32_e32 v0, 2, v26
	v_ashrrev_i32_e32 v6, 2, v6
	v_and_or_b32 v6, v6, -16, v0
	v_ashrrev_i32_e32 v7, 31, v6
	v_lshl_add_u64 v[8:9], v[6:7], 2, s[8:9]
	v_add_u32_e32 v6, 0x400, v6
	v_ashrrev_i32_e32 v7, 31, v6
	v_lshl_add_u64 v[22:23], v[6:7], 2, s[8:9]
	global_load_dwordx4 v[6:9], v[8:9], off
	s_nop 0
	global_load_dwordx4 v[28:31], v[22:23], off
	v_lshlrev_b32_e32 v27, 4, v25
	v_and_or_b32 v0, v27, s1, v0
	v_lshlrev_b32_e32 v0, 2, v0
	v_lshl_add_u64 v[36:37], s[8:9], 0, v[0:1]
	s_movk_i32 s26, 0x1000
	global_load_dwordx4 v[32:35], v0, s[8:9]
	v_add_co_u32_e32 v66, vcc, s26, v36
	s_nop 1
	v_addc_co_u32_e32 v67, vcc, 0, v37, vcc
	global_load_dwordx4 v[36:39], v[66:67], off
	s_waitcnt vmcnt(2)
	v_pk_mul_f32 v[22:23], v[20:21], v[28:29]
	v_pk_mul_f32 v[28:29], v[16:17], v[28:29]
	v_pk_fma_f32 v[16:17], v[16:17], v[6:7], v[22:23]
	v_pk_fma_f32 v[20:21], v[20:21], v[6:7], v[28:29] neg_lo:[0,0,1] neg_hi:[0,0,1]
	s_waitcnt vmcnt(0)
	v_pk_mul_f32 v[6:7], v[12:13], v[36:37]
	v_pk_mul_f32 v[22:23], v[4:5], v[36:37]
	v_pk_fma_f32 v[4:5], v[4:5], v[32:33], v[6:7]
	v_pk_fma_f32 v[12:13], v[12:13], v[32:33], v[22:23] neg_lo:[0,0,1] neg_hi:[0,0,1]
	v_pk_mul_f32 v[6:7], v[18:19], v[30:31]
	v_pk_mul_f32 v[22:23], v[14:15], v[30:31]
	v_pk_fma_f32 v[14:15], v[14:15], v[8:9], v[6:7]
	v_pk_fma_f32 v[18:19], v[18:19], v[8:9], v[22:23] neg_lo:[0,0,1] neg_hi:[0,0,1]
	v_pk_mul_f32 v[6:7], v[10:11], v[38:39]
	v_pk_mul_f32 v[8:9], v[2:3], v[38:39]
	v_pk_fma_f32 v[2:3], v[2:3], v[34:35], v[6:7]
	v_pk_fma_f32 v[10:11], v[10:11], v[34:35], v[8:9] neg_lo:[0,0,1] neg_hi:[0,0,1]
	s_branch .LBB0_605
